# v57: 8 row norms folded into the residual GEMM epilogue (row sums exchanged per panel, x_new normalised from the accumulators, bf16 tile staged through LDS for full-line stores); their norm steps remo
# speedup vs baseline: 1.0659x; 1.0095x over previous
.LBB0_8:
	v_readlane_b32 s6, v254, 61
	s_add_i32 s6, s6, 1
	s_cmp_eq_u32 s6, 37
	v_readlane_b32 s7, v254, 62
	s_cbranch_scc0 .LBB0_9
	s_getpc_b64 s[98:99]

.Lres_src:
	s_lshl_b32 s2, s48, 8
	s_or_b32 s2, s2, s68
	v_lshl_add_u32 v250, v239, 2, s2
	v_lshlrev_b32_e32 v250, 2, v250
	v_lshlrev_b32_e32 v249, 12, v186
	v_add_u32_e32 v248, v249, v250
	s_nop 2
	global_load_dwordx4 v[216:219], v250, s[8:9] offset:0
	global_load_dwordx4 v[220:223], v250, s[8:9] offset:64
	global_load_dwordx4 v[240:243], v250, s[8:9] offset:512
	global_load_dwordx4 v[244:247], v250, s[8:9] offset:576
	v_readlane_b32 s3, v254, 61
	s_mov_b32 s2, -1
	s_cmp_eq_u32 s3, 8
	s_cselect_b32 s2, 2, s2
	s_cmp_eq_u32 s3, 10
	s_cselect_b32 s2, 4, s2
	s_cmp_eq_u32 s3, 20
	s_cselect_b32 s2, 8, s2
	s_cmp_eq_u32 s3, 22
	s_cselect_b32 s2, 9, s2
	s_cmp_eq_u32 s3, 26
	s_cselect_b32 s2, 10, s2
	s_cmp_eq_u32 s3, 28
	s_cselect_b32 s2, 12, s2
	s_cmp_eq_u32 s3, 30
	s_cselect_b32 s2, 13, s2
	s_cmp_eq_u32 s3, 33
	s_cselect_b32 s2, 14, s2
	s_mov_b32 s100, s2
	s_cmp_lt_i32 s2, 0
	s_cbranch_scc0 .Lrf_fused
	global_load_dwordx4 v[130:133], v248, s[10:11] offset:0
	s_add_u32 s14, s10, 0x10000
	s_addc_u32 s15, s11, 0
	global_load_dwordx4 v[134:137], v248, s[14:15] offset:0
	s_add_u32 s14, s10, 0x20000
	s_addc_u32 s15, s11, 0
	global_load_dwordx4 v[138:141], v248, s[14:15] offset:0
	s_add_u32 s14, s10, 0x30000
	s_addc_u32 s15, s11, 0
	global_load_dwordx4 v[142:145], v248, s[14:15] offset:0
	s_add_u32 s14, s10, 0x80000
	s_addc_u32 s15, s11, 0
	global_load_dwordx4 v[146:149], v248, s[14:15] offset:0
	s_add_u32 s14, s10, 0x90000
	s_addc_u32 s15, s11, 0
	global_load_dwordx4 v[150:153], v248, s[14:15] offset:0
	s_add_u32 s14, s10, 0xa0000
	s_addc_u32 s15, s11, 0
	global_load_dwordx4 v[154:157], v248, s[14:15] offset:0
	s_add_u32 s14, s10, 0xb0000
	s_addc_u32 s15, s11, 0
	global_load_dwordx4 v[158:161], v248, s[14:15] offset:0
	global_load_dwordx4 v[162:165], v248, s[10:11] offset:64
	s_add_u32 s14, s10, 0x10000
	s_addc_u32 s15, s11, 0
	global_load_dwordx4 v[188:191], v248, s[14:15] offset:64
	s_add_u32 s14, s10, 0x20000
	s_addc_u32 s15, s11, 0
	global_load_dwordx4 v[192:195], v248, s[14:15] offset:64
	s_add_u32 s14, s10, 0x30000
	s_addc_u32 s15, s11, 0
	global_load_dwordx4 v[196:199], v248, s[14:15] offset:64
	s_add_u32 s14, s10, 0x80000
	s_addc_u32 s15, s11, 0
	global_load_dwordx4 v[200:203], v248, s[14:15] offset:64
	s_add_u32 s14, s10, 0x90000
	s_addc_u32 s15, s11, 0
	global_load_dwordx4 v[204:207], v248, s[14:15] offset:64
	s_add_u32 s14, s10, 0xa0000
	s_addc_u32 s15, s11, 0
	global_load_dwordx4 v[208:211], v248, s[14:15] offset:64
	s_add_u32 s14, s10, 0xb0000
	s_addc_u32 s15, s11, 0
	global_load_dwordx4 v[212:215], v248, s[14:15] offset:64
	s_waitcnt vmcnt(12)
	v_pk_mul_f32 v[216:217], s[28:29], v[216:217]
	v_pk_mul_f32 v[218:219], s[28:29], v[218:219]
	v_pk_mul_f32 v[220:221], s[28:29], v[220:221]
	v_pk_mul_f32 v[222:223], s[28:29], v[222:223]
	v_pk_mul_f32 v[240:241], s[28:29], v[240:241]
	v_pk_mul_f32 v[242:243], s[28:29], v[242:243]
	v_pk_mul_f32 v[244:245], s[28:29], v[244:245]
	v_pk_mul_f32 v[246:247], s[28:29], v[246:247]
	v_pk_fma_f32 v[130:131], v[216:217], v[126:127], v[130:131]
	v_pk_fma_f32 v[132:133], v[218:219], v[128:129], v[132:133]
	v_pk_fma_f32 v[134:135], v[216:217], v[110:111], v[134:135]
	v_pk_fma_f32 v[136:137], v[218:219], v[112:113], v[136:137]
	v_pk_fma_f32 v[138:139], v[216:217], v[94:95], v[138:139]
	v_pk_fma_f32 v[140:141], v[218:219], v[96:97], v[140:141]
	v_pk_fma_f32 v[142:143], v[216:217], v[78:79], v[142:143]
	v_pk_fma_f32 v[144:145], v[218:219], v[80:81], v[144:145]
	global_store_dwordx4 v248, v[130:133], s[12:13] offset:0
	s_add_u32 s2, s12, 0x10000
	s_addc_u32 s3, s13, 0
	global_store_dwordx4 v248, v[134:137], s[2:3] offset:0
	s_add_u32 s2, s12, 0x20000
	s_addc_u32 s3, s13, 0
	global_store_dwordx4 v248, v[138:141], s[2:3] offset:0
	s_add_u32 s2, s12, 0x30000
	s_addc_u32 s3, s13, 0
	global_store_dwordx4 v248, v[142:145], s[2:3] offset:0
	global_load_dwordx4 v[130:133], v248, s[10:11] offset:512
	s_add_u32 s14, s10, 0x10000
	s_addc_u32 s15, s11, 0
	global_load_dwordx4 v[134:137], v248, s[14:15] offset:512
	s_add_u32 s14, s10, 0x20000
	s_addc_u32 s15, s11, 0
	global_load_dwordx4 v[138:141], v248, s[14:15] offset:512
	s_add_u32 s14, s10, 0x30000
	s_addc_u32 s15, s11, 0
	global_load_dwordx4 v[142:145], v248, s[14:15] offset:512
	s_waitcnt vmcnt(16)
	v_pk_fma_f32 v[146:147], v[216:217], v[62:63], v[146:147]
	v_pk_fma_f32 v[148:149], v[218:219], v[64:65], v[148:149]
	v_pk_fma_f32 v[150:151], v[216:217], v[46:47], v[150:151]
	v_pk_fma_f32 v[152:153], v[218:219], v[48:49], v[152:153]
	v_pk_fma_f32 v[154:155], v[216:217], v[30:31], v[154:155]
	v_pk_fma_f32 v[156:157], v[218:219], v[32:33], v[156:157]
	v_pk_fma_f32 v[158:159], v[216:217], v[14:15], v[158:159]
	v_pk_fma_f32 v[160:161], v[218:219], v[16:17], v[160:161]
	s_add_u32 s2, s12, 0x80000
	s_addc_u32 s3, s13, 0
	global_store_dwordx4 v248, v[146:149], s[2:3] offset:0
	s_add_u32 s2, s12, 0x90000
	s_addc_u32 s3, s13, 0
	global_store_dwordx4 v248, v[150:153], s[2:3] offset:0
	s_add_u32 s2, s12, 0xa0000
	s_addc_u32 s3, s13, 0
	global_store_dwordx4 v248, v[154:157], s[2:3] offset:0
	s_add_u32 s2, s12, 0xb0000
	s_addc_u32 s3, s13, 0
	global_store_dwordx4 v248, v[158:161], s[2:3] offset:0
	s_add_u32 s14, s10, 0x80000
	s_addc_u32 s15, s11, 0
	global_load_dwordx4 v[146:149], v248, s[14:15] offset:512
	s_add_u32 s14, s10, 0x90000
	s_addc_u32 s15, s11, 0
	global_load_dwordx4 v[150:153], v248, s[14:15] offset:512
	s_add_u32 s14, s10, 0xa0000
	s_addc_u32 s15, s11, 0
	global_load_dwordx4 v[154:157], v248, s[14:15] offset:512
	s_add_u32 s14, s10, 0xb0000
	s_addc_u32 s15, s11, 0
	global_load_dwordx4 v[158:161], v248, s[14:15] offset:512
	s_waitcnt vmcnt(20)
	v_pk_fma_f32 v[162:163], v[220:221], v[122:123], v[162:163]
	v_pk_fma_f32 v[164:165], v[222:223], v[124:125], v[164:165]
	v_pk_fma_f32 v[188:189], v[220:221], v[106:107], v[188:189]
	v_pk_fma_f32 v[190:191], v[222:223], v[108:109], v[190:191]
	v_pk_fma_f32 v[192:193], v[220:221], v[90:91], v[192:193]
	v_pk_fma_f32 v[194:195], v[222:223], v[92:93], v[194:195]
	v_pk_fma_f32 v[196:197], v[220:221], v[74:75], v[196:197]
	v_pk_fma_f32 v[198:199], v[222:223], v[76:77], v[198:199]
	global_store_dwordx4 v248, v[162:165], s[12:13] offset:64
	s_add_u32 s2, s12, 0x10000
	s_addc_u32 s3, s13, 0
	global_store_dwordx4 v248, v[188:191], s[2:3] offset:64
	s_add_u32 s2, s12, 0x20000
	s_addc_u32 s3, s13, 0
	global_store_dwordx4 v248, v[192:195], s[2:3] offset:64
	s_add_u32 s2, s12, 0x30000
	s_addc_u32 s3, s13, 0
	global_store_dwordx4 v248, v[196:199], s[2:3] offset:64
	global_load_dwordx4 v[162:165], v248, s[10:11] offset:576
	s_add_u32 s14, s10, 0x10000
	s_addc_u32 s15, s11, 0
	global_load_dwordx4 v[188:191], v248, s[14:15] offset:576
	s_add_u32 s14, s10, 0x20000
	s_addc_u32 s15, s11, 0
	global_load_dwordx4 v[192:195], v248, s[14:15] offset:576
	s_add_u32 s14, s10, 0x30000
	s_addc_u32 s15, s11, 0
	global_load_dwordx4 v[196:199], v248, s[14:15] offset:576
	s_waitcnt vmcnt(24)
	v_pk_fma_f32 v[200:201], v[220:221], v[58:59], v[200:201]
	v_pk_fma_f32 v[202:203], v[222:223], v[60:61], v[202:203]
	v_pk_fma_f32 v[204:205], v[220:221], v[42:43], v[204:205]
	v_pk_fma_f32 v[206:207], v[222:223], v[44:45], v[206:207]
	v_pk_fma_f32 v[208:209], v[220:221], v[26:27], v[208:209]
	v_pk_fma_f32 v[210:211], v[222:223], v[28:29], v[210:211]
	v_pk_fma_f32 v[212:213], v[220:221], v[10:11], v[212:213]
	v_pk_fma_f32 v[214:215], v[222:223], v[12:13], v[214:215]
	s_add_u32 s2, s12, 0x80000
	s_addc_u32 s3, s13, 0
	global_store_dwordx4 v248, v[200:203], s[2:3] offset:64
	s_add_u32 s2, s12, 0x90000
	s_addc_u32 s3, s13, 0
	global_store_dwordx4 v248, v[204:207], s[2:3] offset:64
	s_add_u32 s2, s12, 0xa0000
	s_addc_u32 s3, s13, 0
	global_store_dwordx4 v248, v[208:211], s[2:3] offset:64
	s_add_u32 s2, s12, 0xb0000
	s_addc_u32 s3, s13, 0
	global_store_dwordx4 v248, v[212:215], s[2:3] offset:64
	s_add_u32 s14, s10, 0x80000
	s_addc_u32 s15, s11, 0
	global_load_dwordx4 v[200:203], v248, s[14:15] offset:576
	s_add_u32 s14, s10, 0x90000
	s_addc_u32 s15, s11, 0
	global_load_dwordx4 v[204:207], v248, s[14:15] offset:576
	s_add_u32 s14, s10, 0xa0000
	s_addc_u32 s15, s11, 0
	global_load_dwordx4 v[208:211], v248, s[14:15] offset:576
	s_add_u32 s14, s10, 0xb0000
	s_addc_u32 s15, s11, 0
	global_load_dwordx4 v[212:215], v248, s[14:15] offset:576
	s_waitcnt vmcnt(24)
	v_pk_fma_f32 v[130:131], v[240:241], v[118:119], v[130:131]
	v_pk_fma_f32 v[132:133], v[242:243], v[120:121], v[132:133]
	v_pk_fma_f32 v[134:135], v[240:241], v[102:103], v[134:135]
	v_pk_fma_f32 v[136:137], v[242:243], v[104:105], v[136:137]
	v_pk_fma_f32 v[138:139], v[240:241], v[86:87], v[138:139]
	v_pk_fma_f32 v[140:141], v[242:243], v[88:89], v[140:141]
	v_pk_fma_f32 v[142:143], v[240:241], v[70:71], v[142:143]
	v_pk_fma_f32 v[144:145], v[242:243], v[72:73], v[144:145]
	global_store_dwordx4 v248, v[130:133], s[12:13] offset:512
	s_add_u32 s2, s12, 0x10000
	s_addc_u32 s3, s13, 0
	global_store_dwordx4 v248, v[134:137], s[2:3] offset:512
	s_add_u32 s2, s12, 0x20000
	s_addc_u32 s3, s13, 0
	global_store_dwordx4 v248, v[138:141], s[2:3] offset:512
	s_add_u32 s2, s12, 0x30000
	s_addc_u32 s3, s13, 0
	global_store_dwordx4 v248, v[142:145], s[2:3] offset:512
	s_waitcnt vmcnt(20)
	v_pk_fma_f32 v[146:147], v[240:241], v[54:55], v[146:147]
	v_pk_fma_f32 v[148:149], v[242:243], v[56:57], v[148:149]
	v_pk_fma_f32 v[150:151], v[240:241], v[38:39], v[150:151]
	v_pk_fma_f32 v[152:153], v[242:243], v[40:41], v[152:153]
	v_pk_fma_f32 v[154:155], v[240:241], v[22:23], v[154:155]
	v_pk_fma_f32 v[156:157], v[242:243], v[24:25], v[156:157]
	v_pk_fma_f32 v[158:159], v[240:241], v[6:7], v[158:159]
	v_pk_fma_f32 v[160:161], v[242:243], v[8:9], v[160:161]
	s_add_u32 s2, s12, 0x80000
	s_addc_u32 s3, s13, 0
	global_store_dwordx4 v248, v[146:149], s[2:3] offset:512
	s_add_u32 s2, s12, 0x90000
	s_addc_u32 s3, s13, 0
	global_store_dwordx4 v248, v[150:153], s[2:3] offset:512
	s_add_u32 s2, s12, 0xa0000
	s_addc_u32 s3, s13, 0
	global_store_dwordx4 v248, v[154:157], s[2:3] offset:512
	s_add_u32 s2, s12, 0xb0000
	s_addc_u32 s3, s13, 0
	global_store_dwordx4 v248, v[158:161], s[2:3] offset:512
	s_waitcnt vmcnt(16)
	v_pk_fma_f32 v[162:163], v[244:245], v[114:115], v[162:163]
	v_pk_fma_f32 v[164:165], v[246:247], v[116:117], v[164:165]
	v_pk_fma_f32 v[188:189], v[244:245], v[98:99], v[188:189]
	v_pk_fma_f32 v[190:191], v[246:247], v[100:101], v[190:191]
	v_pk_fma_f32 v[192:193], v[244:245], v[82:83], v[192:193]
	v_pk_fma_f32 v[194:195], v[246:247], v[84:85], v[194:195]
	v_pk_fma_f32 v[196:197], v[244:245], v[66:67], v[196:197]
	v_pk_fma_f32 v[198:199], v[246:247], v[68:69], v[198:199]
	global_store_dwordx4 v248, v[162:165], s[12:13] offset:576
	s_add_u32 s2, s12, 0x10000
	s_addc_u32 s3, s13, 0
	global_store_dwordx4 v248, v[188:191], s[2:3] offset:576
	s_add_u32 s2, s12, 0x20000
	s_addc_u32 s3, s13, 0
	global_store_dwordx4 v248, v[192:195], s[2:3] offset:576
	s_add_u32 s2, s12, 0x30000
	s_addc_u32 s3, s13, 0
	global_store_dwordx4 v248, v[196:199], s[2:3] offset:576
	s_waitcnt vmcnt(12)
	v_pk_fma_f32 v[200:201], v[244:245], v[50:51], v[200:201]
	v_pk_fma_f32 v[202:203], v[246:247], v[52:53], v[202:203]
	v_pk_fma_f32 v[204:205], v[244:245], v[34:35], v[204:205]
	v_pk_fma_f32 v[206:207], v[246:247], v[36:37], v[206:207]
	v_pk_fma_f32 v[208:209], v[244:245], v[18:19], v[208:209]
	v_pk_fma_f32 v[210:211], v[246:247], v[20:21], v[210:211]
	v_pk_fma_f32 v[212:213], v[244:245], v[2:3], v[212:213]
	v_pk_fma_f32 v[214:215], v[246:247], v[4:5], v[214:215]
	s_add_u32 s2, s12, 0x80000
	s_addc_u32 s3, s13, 0
	global_store_dwordx4 v248, v[200:203], s[2:3] offset:576
	s_add_u32 s2, s12, 0x90000
	s_addc_u32 s3, s13, 0
	global_store_dwordx4 v248, v[204:207], s[2:3] offset:576
	s_add_u32 s2, s12, 0xa0000
	s_addc_u32 s3, s13, 0
	global_store_dwordx4 v248, v[208:211], s[2:3] offset:576
	s_add_u32 s2, s12, 0xb0000
	s_addc_u32 s3, s13, 0
	global_store_dwordx4 v248, v[212:215], s[2:3] offset:576
	s_branch .LBB0_561
.Lrf_fused:
	global_load_dwordx4 v[130:133], v248, s[10:11] offset:0
	s_add_u32 s14, s10, 0x10000
	s_addc_u32 s15, s11, 0
	global_load_dwordx4 v[134:137], v248, s[14:15] offset:0
	s_add_u32 s14, s10, 0x20000
	s_addc_u32 s15, s11, 0
	global_load_dwordx4 v[138:141], v248, s[14:15] offset:0
	s_add_u32 s14, s10, 0x30000
	s_addc_u32 s15, s11, 0
	global_load_dwordx4 v[142:145], v248, s[14:15] offset:0
	s_add_u32 s14, s10, 0x80000
	s_addc_u32 s15, s11, 0
	global_load_dwordx4 v[146:149], v248, s[14:15] offset:0
	s_add_u32 s14, s10, 0x90000
	s_addc_u32 s15, s11, 0
	global_load_dwordx4 v[150:153], v248, s[14:15] offset:0
	s_add_u32 s14, s10, 0xa0000
	s_addc_u32 s15, s11, 0
	global_load_dwordx4 v[154:157], v248, s[14:15] offset:0
	s_add_u32 s14, s10, 0xb0000
	s_addc_u32 s15, s11, 0
	global_load_dwordx4 v[158:161], v248, s[14:15] offset:0
	global_load_dwordx4 v[162:165], v248, s[10:11] offset:64
	s_add_u32 s14, s10, 0x10000
	s_addc_u32 s15, s11, 0
	global_load_dwordx4 v[188:191], v248, s[14:15] offset:64
	s_add_u32 s14, s10, 0x20000
	s_addc_u32 s15, s11, 0
	global_load_dwordx4 v[192:195], v248, s[14:15] offset:64
	s_add_u32 s14, s10, 0x30000
	s_addc_u32 s15, s11, 0
	global_load_dwordx4 v[196:199], v248, s[14:15] offset:64
	s_add_u32 s14, s10, 0x80000
	s_addc_u32 s15, s11, 0
	global_load_dwordx4 v[200:203], v248, s[14:15] offset:64
	s_add_u32 s14, s10, 0x90000
	s_addc_u32 s15, s11, 0
	global_load_dwordx4 v[204:207], v248, s[14:15] offset:64
	s_add_u32 s14, s10, 0xa0000
	s_addc_u32 s15, s11, 0
	global_load_dwordx4 v[208:211], v248, s[14:15] offset:64
	s_add_u32 s14, s10, 0xb0000
	s_addc_u32 s15, s11, 0
	global_load_dwordx4 v[212:215], v248, s[14:15] offset:64
	s_waitcnt vmcnt(12)
	v_pk_mul_f32 v[216:217], s[28:29], v[216:217]
	v_pk_mul_f32 v[218:219], s[28:29], v[218:219]
	v_pk_mul_f32 v[220:221], s[28:29], v[220:221]
	v_pk_mul_f32 v[222:223], s[28:29], v[222:223]
	v_pk_mul_f32 v[240:241], s[28:29], v[240:241]
	v_pk_mul_f32 v[242:243], s[28:29], v[242:243]
	v_pk_mul_f32 v[244:245], s[28:29], v[244:245]
	v_pk_mul_f32 v[246:247], s[28:29], v[246:247]
	v_pk_fma_f32 v[126:127], v[216:217], v[126:127], v[130:131]
	v_pk_fma_f32 v[128:129], v[218:219], v[128:129], v[132:133]
	v_pk_fma_f32 v[110:111], v[216:217], v[110:111], v[134:135]
	v_pk_fma_f32 v[112:113], v[218:219], v[112:113], v[136:137]
	v_pk_fma_f32 v[94:95], v[216:217], v[94:95], v[138:139]
	v_pk_fma_f32 v[96:97], v[218:219], v[96:97], v[140:141]
	v_pk_fma_f32 v[78:79], v[216:217], v[78:79], v[142:143]
	v_pk_fma_f32 v[80:81], v[218:219], v[80:81], v[144:145]
	global_load_dwordx4 v[130:133], v248, s[10:11] offset:512
	s_add_u32 s14, s10, 0x10000
	s_addc_u32 s15, s11, 0
	global_load_dwordx4 v[134:137], v248, s[14:15] offset:512
	s_add_u32 s14, s10, 0x20000
	s_addc_u32 s15, s11, 0
	global_load_dwordx4 v[138:141], v248, s[14:15] offset:512
	s_add_u32 s14, s10, 0x30000
	s_addc_u32 s15, s11, 0
	global_load_dwordx4 v[142:145], v248, s[14:15] offset:512
	s_waitcnt vmcnt(12)
	v_pk_fma_f32 v[62:63], v[216:217], v[62:63], v[146:147]
	v_pk_fma_f32 v[64:65], v[218:219], v[64:65], v[148:149]
	v_pk_fma_f32 v[46:47], v[216:217], v[46:47], v[150:151]
	v_pk_fma_f32 v[48:49], v[218:219], v[48:49], v[152:153]
	v_pk_fma_f32 v[30:31], v[216:217], v[30:31], v[154:155]
	v_pk_fma_f32 v[32:33], v[218:219], v[32:33], v[156:157]
	v_pk_fma_f32 v[14:15], v[216:217], v[14:15], v[158:159]
	v_pk_fma_f32 v[16:17], v[218:219], v[16:17], v[160:161]
	s_add_u32 s14, s10, 0x80000
	s_addc_u32 s15, s11, 0
	global_load_dwordx4 v[146:149], v248, s[14:15] offset:512
	s_add_u32 s14, s10, 0x90000
	s_addc_u32 s15, s11, 0
	global_load_dwordx4 v[150:153], v248, s[14:15] offset:512
	s_add_u32 s14, s10, 0xa0000
	s_addc_u32 s15, s11, 0
	global_load_dwordx4 v[154:157], v248, s[14:15] offset:512
	s_add_u32 s14, s10, 0xb0000
	s_addc_u32 s15, s11, 0
	global_load_dwordx4 v[158:161], v248, s[14:15] offset:512
	s_waitcnt vmcnt(12)
	v_pk_fma_f32 v[122:123], v[220:221], v[122:123], v[162:163]
	v_pk_fma_f32 v[124:125], v[222:223], v[124:125], v[164:165]
	v_pk_fma_f32 v[106:107], v[220:221], v[106:107], v[188:189]
	v_pk_fma_f32 v[108:109], v[222:223], v[108:109], v[190:191]
	v_pk_fma_f32 v[90:91], v[220:221], v[90:91], v[192:193]
	v_pk_fma_f32 v[92:93], v[222:223], v[92:93], v[194:195]
	v_pk_fma_f32 v[74:75], v[220:221], v[74:75], v[196:197]
	v_pk_fma_f32 v[76:77], v[222:223], v[76:77], v[198:199]
	global_load_dwordx4 v[162:165], v248, s[10:11] offset:576
	s_add_u32 s14, s10, 0x10000
	s_addc_u32 s15, s11, 0
	global_load_dwordx4 v[188:191], v248, s[14:15] offset:576
	s_add_u32 s14, s10, 0x20000
	s_addc_u32 s15, s11, 0
	global_load_dwordx4 v[192:195], v248, s[14:15] offset:576
	s_add_u32 s14, s10, 0x30000
	s_addc_u32 s15, s11, 0
	global_load_dwordx4 v[196:199], v248, s[14:15] offset:576
	s_waitcnt vmcnt(12)
	v_pk_fma_f32 v[58:59], v[220:221], v[58:59], v[200:201]
	v_pk_fma_f32 v[60:61], v[222:223], v[60:61], v[202:203]
	v_pk_fma_f32 v[42:43], v[220:221], v[42:43], v[204:205]
	v_pk_fma_f32 v[44:45], v[222:223], v[44:45], v[206:207]
	v_pk_fma_f32 v[26:27], v[220:221], v[26:27], v[208:209]
	v_pk_fma_f32 v[28:29], v[222:223], v[28:29], v[210:211]
	v_pk_fma_f32 v[10:11], v[220:221], v[10:11], v[212:213]
	v_pk_fma_f32 v[12:13], v[222:223], v[12:13], v[214:215]
	s_add_u32 s14, s10, 0x80000
	s_addc_u32 s15, s11, 0
	global_load_dwordx4 v[200:203], v248, s[14:15] offset:576
	s_add_u32 s14, s10, 0x90000
	s_addc_u32 s15, s11, 0
	global_load_dwordx4 v[204:207], v248, s[14:15] offset:576
	s_add_u32 s14, s10, 0xa0000
	s_addc_u32 s15, s11, 0
	global_load_dwordx4 v[208:211], v248, s[14:15] offset:576
	s_add_u32 s14, s10, 0xb0000
	s_addc_u32 s15, s11, 0
	global_load_dwordx4 v[212:215], v248, s[14:15] offset:576
	s_waitcnt vmcnt(12)
	v_pk_fma_f32 v[118:119], v[240:241], v[118:119], v[130:131]
	v_pk_fma_f32 v[120:121], v[242:243], v[120:121], v[132:133]
	v_pk_fma_f32 v[102:103], v[240:241], v[102:103], v[134:135]
	v_pk_fma_f32 v[104:105], v[242:243], v[104:105], v[136:137]
	v_pk_fma_f32 v[86:87], v[240:241], v[86:87], v[138:139]
	v_pk_fma_f32 v[88:89], v[242:243], v[88:89], v[140:141]
	v_pk_fma_f32 v[70:71], v[240:241], v[70:71], v[142:143]
	v_pk_fma_f32 v[72:73], v[242:243], v[72:73], v[144:145]
	s_waitcnt vmcnt(8)
	v_pk_fma_f32 v[54:55], v[240:241], v[54:55], v[146:147]
	v_pk_fma_f32 v[56:57], v[242:243], v[56:57], v[148:149]
	v_pk_fma_f32 v[38:39], v[240:241], v[38:39], v[150:151]
	v_pk_fma_f32 v[40:41], v[242:243], v[40:41], v[152:153]
	v_pk_fma_f32 v[22:23], v[240:241], v[22:23], v[154:155]
	v_pk_fma_f32 v[24:25], v[242:243], v[24:25], v[156:157]
	v_pk_fma_f32 v[6:7], v[240:241], v[6:7], v[158:159]
	v_pk_fma_f32 v[8:9], v[242:243], v[8:9], v[160:161]
	s_waitcnt vmcnt(4)
	v_pk_fma_f32 v[114:115], v[244:245], v[114:115], v[162:163]
	v_pk_fma_f32 v[116:117], v[246:247], v[116:117], v[164:165]
	v_pk_fma_f32 v[98:99], v[244:245], v[98:99], v[188:189]
	v_pk_fma_f32 v[100:101], v[246:247], v[100:101], v[190:191]
	v_pk_fma_f32 v[82:83], v[244:245], v[82:83], v[192:193]
	v_pk_fma_f32 v[84:85], v[246:247], v[84:85], v[194:195]
	v_pk_fma_f32 v[66:67], v[244:245], v[66:67], v[196:197]
	v_pk_fma_f32 v[68:69], v[246:247], v[68:69], v[198:199]
	s_waitcnt vmcnt(0)
	v_pk_fma_f32 v[50:51], v[244:245], v[50:51], v[200:201]
	v_pk_fma_f32 v[52:53], v[246:247], v[52:53], v[202:203]
	v_pk_fma_f32 v[34:35], v[244:245], v[34:35], v[204:205]
	v_pk_fma_f32 v[36:37], v[246:247], v[36:37], v[206:207]
	v_pk_fma_f32 v[18:19], v[244:245], v[18:19], v[208:209]
	v_pk_fma_f32 v[20:21], v[246:247], v[20:21], v[210:211]
	v_pk_fma_f32 v[2:3], v[244:245], v[2:3], v[212:213]
	v_pk_fma_f32 v[4:5], v[246:247], v[4:5], v[214:215]
	s_mov_b32 s2, s100
	s_mov_b64 s[100:101], s[12:13]
	s_ashr_i32 s8, s2, 2
	s_and_b32 s9, s2, 3
	s_mul_i32 s10, s8, 3
	s_add_i32 s11, s10, s9
	s_lshl_b32 s12, s17, 8
	s_sub_i32 s12, s12, 0x1800
	s_max_i32 s12, s12, 0
	s_lshr_b32 s12, s12, 11
	s_add_i32 s10, s10, s12
	s_mul_i32 s10, s10, 0x9000
	s_mul_i32 s9, s9, 0x3000
	s_add_i32 s10, s10, s9
	s_add_i32 s10, s10, 0x100000
	v_readlane_b32 s14, v255, 7
	v_readlane_b32 s15, v255, 8
	s_add_u32 s14, s14, s10
	s_addc_u32 s15, s15, 0
	s_add_u32 s12, s14, 0x1000
	s_addc_u32 s13, s15, 0
	v_readlane_b32 s8, v255, 14
	v_readlane_b32 s9, v255, 15
	s_load_dwordx2 s[8:9], s[8:9], 0x58
	s_lshl_b32 s11, s11, 12
	s_waitcnt lgkmcnt(0)
	s_add_u32 s8, s8, s11
	s_addc_u32 s9, s9, 0
	global_load_dwordx4 v[130:133], v250, s[8:9] offset:0
	global_load_dwordx4 v[146:149], v250, s[12:13] offset:0
	global_load_dwordx4 v[162:165], v250, s[14:15] offset:0
	global_load_dwordx4 v[134:137], v250, s[8:9] offset:64
	global_load_dwordx4 v[150:153], v250, s[12:13] offset:64
	global_load_dwordx4 v[188:191], v250, s[14:15] offset:64
	global_load_dwordx4 v[138:141], v250, s[8:9] offset:512
	global_load_dwordx4 v[154:157], v250, s[12:13] offset:512
	global_load_dwordx4 v[192:195], v250, s[14:15] offset:512
	global_load_dwordx4 v[142:145], v250, s[8:9] offset:576
	global_load_dwordx4 v[158:161], v250, s[12:13] offset:576
	global_load_dwordx4 v[196:199], v250, s[14:15] offset:576
	v_mul_f32_e32 v200, v126, v126
	v_fmac_f32_e32 v200, v127, v127
	v_fmac_f32_e32 v200, v128, v128
	v_fmac_f32_e32 v200, v129, v129
	v_fmac_f32_e32 v200, v122, v122
	v_fmac_f32_e32 v200, v123, v123
	v_fmac_f32_e32 v200, v124, v124
	v_fmac_f32_e32 v200, v125, v125
	v_fmac_f32_e32 v200, v118, v118
	v_fmac_f32_e32 v200, v119, v119
	v_fmac_f32_e32 v200, v120, v120
	v_fmac_f32_e32 v200, v121, v121
	v_fmac_f32_e32 v200, v114, v114
	v_fmac_f32_e32 v200, v115, v115
	v_fmac_f32_e32 v200, v116, v116
	v_fmac_f32_e32 v200, v117, v117
	v_mul_f32_e32 v201, v110, v110
	v_fmac_f32_e32 v201, v111, v111
	v_fmac_f32_e32 v201, v112, v112
	v_fmac_f32_e32 v201, v113, v113
	v_fmac_f32_e32 v201, v106, v106
	v_fmac_f32_e32 v201, v107, v107
	v_fmac_f32_e32 v201, v108, v108
	v_fmac_f32_e32 v201, v109, v109
	v_fmac_f32_e32 v201, v102, v102
	v_fmac_f32_e32 v201, v103, v103
	v_fmac_f32_e32 v201, v104, v104
	v_fmac_f32_e32 v201, v105, v105
	v_fmac_f32_e32 v201, v98, v98
	v_fmac_f32_e32 v201, v99, v99
	v_fmac_f32_e32 v201, v100, v100
	v_fmac_f32_e32 v201, v101, v101
	v_mul_f32_e32 v202, v94, v94
	v_fmac_f32_e32 v202, v95, v95
	v_fmac_f32_e32 v202, v96, v96
	v_fmac_f32_e32 v202, v97, v97
	v_fmac_f32_e32 v202, v90, v90
	v_fmac_f32_e32 v202, v91, v91
	v_fmac_f32_e32 v202, v92, v92
	v_fmac_f32_e32 v202, v93, v93
	v_fmac_f32_e32 v202, v86, v86
	v_fmac_f32_e32 v202, v87, v87
	v_fmac_f32_e32 v202, v88, v88
	v_fmac_f32_e32 v202, v89, v89
	v_fmac_f32_e32 v202, v82, v82
	v_fmac_f32_e32 v202, v83, v83
	v_fmac_f32_e32 v202, v84, v84
	v_fmac_f32_e32 v202, v85, v85
	v_mul_f32_e32 v203, v78, v78
	v_fmac_f32_e32 v203, v79, v79
	v_fmac_f32_e32 v203, v80, v80
	v_fmac_f32_e32 v203, v81, v81
	v_fmac_f32_e32 v203, v74, v74
	v_fmac_f32_e32 v203, v75, v75
	v_fmac_f32_e32 v203, v76, v76
	v_fmac_f32_e32 v203, v77, v77
	v_fmac_f32_e32 v203, v70, v70
	v_fmac_f32_e32 v203, v71, v71
	v_fmac_f32_e32 v203, v72, v72
	v_fmac_f32_e32 v203, v73, v73
	v_fmac_f32_e32 v203, v66, v66
	v_fmac_f32_e32 v203, v67, v67
	v_fmac_f32_e32 v203, v68, v68
	v_fmac_f32_e32 v203, v69, v69
	v_mul_f32_e32 v204, v62, v62
	v_fmac_f32_e32 v204, v63, v63
	v_fmac_f32_e32 v204, v64, v64
	v_fmac_f32_e32 v204, v65, v65
	v_fmac_f32_e32 v204, v58, v58
	v_fmac_f32_e32 v204, v59, v59
	v_fmac_f32_e32 v204, v60, v60
	v_fmac_f32_e32 v204, v61, v61
	v_fmac_f32_e32 v204, v54, v54
	v_fmac_f32_e32 v204, v55, v55
	v_fmac_f32_e32 v204, v56, v56
	v_fmac_f32_e32 v204, v57, v57
	v_fmac_f32_e32 v204, v50, v50
	v_fmac_f32_e32 v204, v51, v51
	v_fmac_f32_e32 v204, v52, v52
	v_fmac_f32_e32 v204, v53, v53
	v_mul_f32_e32 v205, v46, v46
	v_fmac_f32_e32 v205, v47, v47
	v_fmac_f32_e32 v205, v48, v48
	v_fmac_f32_e32 v205, v49, v49
	v_fmac_f32_e32 v205, v42, v42
	v_fmac_f32_e32 v205, v43, v43
	v_fmac_f32_e32 v205, v44, v44
	v_fmac_f32_e32 v205, v45, v45
	v_fmac_f32_e32 v205, v38, v38
	v_fmac_f32_e32 v205, v39, v39
	v_fmac_f32_e32 v205, v40, v40
	v_fmac_f32_e32 v205, v41, v41
	v_fmac_f32_e32 v205, v34, v34
	v_fmac_f32_e32 v205, v35, v35
	v_fmac_f32_e32 v205, v36, v36
	v_fmac_f32_e32 v205, v37, v37
	v_mul_f32_e32 v206, v30, v30
	v_fmac_f32_e32 v206, v31, v31
	v_fmac_f32_e32 v206, v32, v32
	v_fmac_f32_e32 v206, v33, v33
	v_fmac_f32_e32 v206, v26, v26
	v_fmac_f32_e32 v206, v27, v27
	v_fmac_f32_e32 v206, v28, v28
	v_fmac_f32_e32 v206, v29, v29
	v_fmac_f32_e32 v206, v22, v22
	v_fmac_f32_e32 v206, v23, v23
	v_fmac_f32_e32 v206, v24, v24
	v_fmac_f32_e32 v206, v25, v25
	v_fmac_f32_e32 v206, v18, v18
	v_fmac_f32_e32 v206, v19, v19
	v_fmac_f32_e32 v206, v20, v20
	v_fmac_f32_e32 v206, v21, v21
	v_mul_f32_e32 v207, v14, v14
	v_fmac_f32_e32 v207, v15, v15
	v_fmac_f32_e32 v207, v16, v16
	v_fmac_f32_e32 v207, v17, v17
	v_fmac_f32_e32 v207, v10, v10
	v_fmac_f32_e32 v207, v11, v11
	v_fmac_f32_e32 v207, v12, v12
	v_fmac_f32_e32 v207, v13, v13
	v_fmac_f32_e32 v207, v6, v6
	v_fmac_f32_e32 v207, v7, v7
	v_fmac_f32_e32 v207, v8, v8
	v_fmac_f32_e32 v207, v9, v9
	v_fmac_f32_e32 v207, v2, v2
	v_fmac_f32_e32 v207, v3, v3
	v_fmac_f32_e32 v207, v4, v4
	v_fmac_f32_e32 v207, v5, v5
	v_mov_b32_e32 v208, v200
	v_mov_b32_e32 v209, v201
	v_mov_b32_e32 v210, v202
	v_mov_b32_e32 v211, v203
	v_mov_b32_e32 v212, v204
	v_mov_b32_e32 v213, v205
	v_mov_b32_e32 v214, v206
	v_mov_b32_e32 v215, v207
	s_nop 1
	v_permlane16_swap_b32_e32 v208, v200
	v_permlane16_swap_b32_e32 v209, v201
	v_permlane16_swap_b32_e32 v210, v202
	v_permlane16_swap_b32_e32 v211, v203
	v_permlane16_swap_b32_e32 v212, v204
	v_permlane16_swap_b32_e32 v213, v205
	v_permlane16_swap_b32_e32 v214, v206
	v_permlane16_swap_b32_e32 v215, v207
	v_add_f32_e32 v200, v200, v208
	v_add_f32_e32 v201, v201, v209
	v_add_f32_e32 v202, v202, v210
	v_add_f32_e32 v203, v203, v211
	v_add_f32_e32 v204, v204, v212
	v_add_f32_e32 v205, v205, v213
	v_add_f32_e32 v206, v206, v214
	v_add_f32_e32 v207, v207, v215
	v_mov_b32_e32 v208, v200
	v_mov_b32_e32 v209, v201
	v_mov_b32_e32 v210, v202
	v_mov_b32_e32 v211, v203
	v_mov_b32_e32 v212, v204
	v_mov_b32_e32 v213, v205
	v_mov_b32_e32 v214, v206
	v_mov_b32_e32 v215, v207
	s_nop 1
	v_permlane32_swap_b32_e32 v208, v200
	v_permlane32_swap_b32_e32 v209, v201
	v_permlane32_swap_b32_e32 v210, v202
	v_permlane32_swap_b32_e32 v211, v203
	v_permlane32_swap_b32_e32 v212, v204
	v_permlane32_swap_b32_e32 v213, v205
	v_permlane32_swap_b32_e32 v214, v206
	v_permlane32_swap_b32_e32 v215, v207
	v_add_f32_e32 v200, v200, v208
	v_add_f32_e32 v201, v201, v209
	v_add_f32_e32 v202, v202, v210
	v_add_f32_e32 v203, v203, v211
	v_add_f32_e32 v204, v204, v212
	v_add_f32_e32 v205, v205, v213
	v_add_f32_e32 v206, v206, v214
	v_add_f32_e32 v207, v207, v215
	v_readlane_b32 s3, v254, 63
	s_lshl_b32 s2, s3, 9
	s_add_i32 s2, s2, 0x20000
	v_lshlrev_b32_e32 v251, 2, v235
	v_add_u32_e32 v252, s2, v251
	ds_write_b32 v252, v200 offset:0
	ds_write_b32 v252, v201 offset:64
	ds_write_b32 v252, v202 offset:128
	ds_write_b32 v252, v203 offset:192
	ds_write_b32 v252, v204 offset:256
	ds_write_b32 v252, v205 offset:320
	ds_write_b32 v252, v206 offset:384
	ds_write_b32 v252, v207 offset:448
	s_lshl_b32 s2, s67, 5
	s_add_i32 s2, s2, 0x20000
	v_add_u32_e32 v252, s2, v251
	s_waitcnt lgkmcnt(0)
	s_barrier
	ds_read_b32 v216, v252 offset:0
	ds_read_b32 v217, v252 offset:512
	ds_read_b32 v218, v252 offset:1024
	ds_read_b32 v219, v252 offset:1536
	ds_read_b32 v220, v252 offset:64
	ds_read_b32 v221, v252 offset:576
	ds_read_b32 v222, v252 offset:1088
	ds_read_b32 v223, v252 offset:1600
	ds_read_b32 v240, v252 offset:128
	ds_read_b32 v241, v252 offset:640
	ds_read_b32 v242, v252 offset:1152
	ds_read_b32 v243, v252 offset:1664
	ds_read_b32 v244, v252 offset:192
	ds_read_b32 v245, v252 offset:704
	ds_read_b32 v246, v252 offset:1216
	ds_read_b32 v247, v252 offset:1728
	s_waitcnt lgkmcnt(0)
	v_add_f32_e32 v200, v216, v217
	v_add_f32_e32 v208, v218, v219
	v_add_f32_e32 v201, v220, v221
	v_add_f32_e32 v209, v222, v223
	v_add_f32_e32 v202, v240, v241
	v_add_f32_e32 v210, v242, v243
	v_add_f32_e32 v203, v244, v245
	v_add_f32_e32 v211, v246, v247
	v_add_f32_e32 v200, v200, v208
	v_add_f32_e32 v201, v201, v209
	v_add_f32_e32 v202, v202, v210
	v_add_f32_e32 v203, v203, v211
	ds_read_b32 v216, v252 offset:256
	ds_read_b32 v217, v252 offset:768
	ds_read_b32 v218, v252 offset:1280
	ds_read_b32 v219, v252 offset:1792
	ds_read_b32 v220, v252 offset:320
	ds_read_b32 v221, v252 offset:832
	ds_read_b32 v222, v252 offset:1344
	ds_read_b32 v223, v252 offset:1856
	ds_read_b32 v240, v252 offset:384
	ds_read_b32 v241, v252 offset:896
	ds_read_b32 v242, v252 offset:1408
	ds_read_b32 v243, v252 offset:1920
	ds_read_b32 v244, v252 offset:448
	ds_read_b32 v245, v252 offset:960
	ds_read_b32 v246, v252 offset:1472
	ds_read_b32 v247, v252 offset:1984
	s_waitcnt lgkmcnt(0)
	v_add_f32_e32 v204, v216, v217
	v_add_f32_e32 v212, v218, v219
	v_add_f32_e32 v205, v220, v221
	v_add_f32_e32 v213, v222, v223
	v_add_f32_e32 v206, v240, v241
	v_add_f32_e32 v214, v242, v243
	v_add_f32_e32 v207, v244, v245
	v_add_f32_e32 v215, v246, v247
	v_add_f32_e32 v204, v204, v212
	v_add_f32_e32 v205, v205, v213
	v_add_f32_e32 v206, v206, v214
	v_add_f32_e32 v207, v207, v215
	v_lshlrev_b32_e32 v253, 4, v186
	v_readlane_b32 s10, v255, 7
	v_readlane_b32 s11, v255, 8
	s_add_u32 s10, s10, 0x20000
	s_addc_u32 s11, s11, 0
	s_cmp_lg_u32 s68, 0
	s_cbranch_scc1 .Lrf_nopub
	s_lshl_b32 s2, s48, 2
	s_add_u32 s8, s10, s2
	s_addc_u32 s9, s11, 0
	s_mov_b64 s[14:15], exec
	s_mov_b64 exec, 0xffff
	global_store_dword v253, v200, s[8:9] offset:0
	global_store_dword v253, v201, s[8:9] offset:256
	global_store_dword v253, v202, s[8:9] offset:512
	global_store_dword v253, v203, s[8:9] offset:768
	global_store_dword v253, v204, s[8:9] offset:2048
	global_store_dword v253, v205, s[8:9] offset:2304
	global_store_dword v253, v206, s[8:9] offset:2560
	global_store_dword v253, v207, s[8:9] offset:2816
	s_mov_b64 exec, s[14:15]
.Lrf_nopub:
	s_nop 0
	global_store_dwordx4 v248, v[126:129], s[100:101] offset:0
	s_add_u32 s8, s100, 0x10000
	s_addc_u32 s9, s101, 0
	global_store_dwordx4 v248, v[110:113], s[8:9] offset:0
	s_add_u32 s8, s100, 0x20000
	s_addc_u32 s9, s101, 0
	global_store_dwordx4 v248, v[94:97], s[8:9] offset:0
	s_add_u32 s8, s100, 0x30000
	s_addc_u32 s9, s101, 0
	global_store_dwordx4 v248, v[78:81], s[8:9] offset:0
	s_add_u32 s8, s100, 0x80000
	s_addc_u32 s9, s101, 0
	global_store_dwordx4 v248, v[62:65], s[8:9] offset:0
	s_add_u32 s8, s100, 0x90000
	s_addc_u32 s9, s101, 0
	global_store_dwordx4 v248, v[46:49], s[8:9] offset:0
	s_add_u32 s8, s100, 0xa0000
	s_addc_u32 s9, s101, 0
	global_store_dwordx4 v248, v[30:33], s[8:9] offset:0
	s_add_u32 s8, s100, 0xb0000
	s_addc_u32 s9, s101, 0
	global_store_dwordx4 v248, v[14:17], s[8:9] offset:0
	global_store_dwordx4 v248, v[122:125], s[100:101] offset:64
	s_add_u32 s8, s100, 0x10000
	s_addc_u32 s9, s101, 0
	global_store_dwordx4 v248, v[106:109], s[8:9] offset:64
	s_add_u32 s8, s100, 0x20000
	s_addc_u32 s9, s101, 0
	global_store_dwordx4 v248, v[90:93], s[8:9] offset:64
	s_add_u32 s8, s100, 0x30000
	s_addc_u32 s9, s101, 0
	global_store_dwordx4 v248, v[74:77], s[8:9] offset:64
	s_add_u32 s8, s100, 0x80000
	s_addc_u32 s9, s101, 0
	global_store_dwordx4 v248, v[58:61], s[8:9] offset:64
	s_add_u32 s8, s100, 0x90000
	s_addc_u32 s9, s101, 0
	global_store_dwordx4 v248, v[42:45], s[8:9] offset:64
	s_add_u32 s8, s100, 0xa0000
	s_addc_u32 s9, s101, 0
	global_store_dwordx4 v248, v[26:29], s[8:9] offset:64
	s_add_u32 s8, s100, 0xb0000
	s_addc_u32 s9, s101, 0
	global_store_dwordx4 v248, v[10:13], s[8:9] offset:64
	global_store_dwordx4 v248, v[118:121], s[100:101] offset:512
	s_add_u32 s8, s100, 0x10000
	s_addc_u32 s9, s101, 0
	global_store_dwordx4 v248, v[102:105], s[8:9] offset:512
	s_add_u32 s8, s100, 0x20000
	s_addc_u32 s9, s101, 0
	global_store_dwordx4 v248, v[86:89], s[8:9] offset:512
	s_add_u32 s8, s100, 0x30000
	s_addc_u32 s9, s101, 0
	global_store_dwordx4 v248, v[70:73], s[8:9] offset:512
	s_add_u32 s8, s100, 0x80000
	s_addc_u32 s9, s101, 0
	global_store_dwordx4 v248, v[54:57], s[8:9] offset:512
	s_add_u32 s8, s100, 0x90000
	s_addc_u32 s9, s101, 0
	global_store_dwordx4 v248, v[38:41], s[8:9] offset:512
	s_add_u32 s8, s100, 0xa0000
	s_addc_u32 s9, s101, 0
	global_store_dwordx4 v248, v[22:25], s[8:9] offset:512
	s_add_u32 s8, s100, 0xb0000
	s_addc_u32 s9, s101, 0
	global_store_dwordx4 v248, v[6:9], s[8:9] offset:512
	global_store_dwordx4 v248, v[114:117], s[100:101] offset:576
	s_add_u32 s8, s100, 0x10000
	s_addc_u32 s9, s101, 0
	global_store_dwordx4 v248, v[98:101], s[8:9] offset:576
	s_add_u32 s8, s100, 0x20000
	s_addc_u32 s9, s101, 0
	global_store_dwordx4 v248, v[82:85], s[8:9] offset:576
	s_add_u32 s8, s100, 0x30000
	s_addc_u32 s9, s101, 0
	global_store_dwordx4 v248, v[66:69], s[8:9] offset:576
	s_add_u32 s8, s100, 0x80000
	s_addc_u32 s9, s101, 0
	global_store_dwordx4 v248, v[50:53], s[8:9] offset:576
	s_add_u32 s8, s100, 0x90000
	s_addc_u32 s9, s101, 0
	global_store_dwordx4 v248, v[34:37], s[8:9] offset:576
	s_add_u32 s8, s100, 0xa0000
	s_addc_u32 s9, s101, 0
	global_store_dwordx4 v248, v[18:21], s[8:9] offset:576
	s_add_u32 s8, s100, 0xb0000
	s_addc_u32 s9, s101, 0
	global_store_dwordx4 v248, v[2:5], s[8:9] offset:576
	s_waitcnt vmcnt(32)
	v_add_f32_e32 v146, 1.0, v146
	v_add_f32_e32 v147, 1.0, v147
	v_add_f32_e32 v148, 1.0, v148
	v_add_f32_e32 v149, 1.0, v149
	v_add_f32_e32 v150, 1.0, v150
	v_add_f32_e32 v151, 1.0, v151
	v_add_f32_e32 v152, 1.0, v152
	v_add_f32_e32 v153, 1.0, v153
	v_add_f32_e32 v154, 1.0, v154
	v_add_f32_e32 v155, 1.0, v155
	v_add_f32_e32 v156, 1.0, v156
	v_add_f32_e32 v157, 1.0, v157
	v_add_f32_e32 v158, 1.0, v158
	v_add_f32_e32 v159, 1.0, v159
	v_add_f32_e32 v160, 1.0, v160
	v_add_f32_e32 v161, 1.0, v161
	v_mul_f32_e32 v146, v130, v146
	v_mul_f32_e32 v147, v131, v147
	v_mul_f32_e32 v148, v132, v148
	v_mul_f32_e32 v149, v133, v149
	v_mul_f32_e32 v150, v134, v150
	v_mul_f32_e32 v151, v135, v151
	v_mul_f32_e32 v152, v136, v152
	v_mul_f32_e32 v153, v137, v153
	v_mul_f32_e32 v154, v138, v154
	v_mul_f32_e32 v155, v139, v155
	v_mul_f32_e32 v156, v140, v156
	v_mul_f32_e32 v157, v141, v157
	v_mul_f32_e32 v158, v142, v158
	v_mul_f32_e32 v159, v143, v159
	v_mul_f32_e32 v160, v144, v160
	v_mul_f32_e32 v161, v145, v161
	s_barrier
	s_cmp_lg_u32 s3, 0
	s_cbranch_scc1 .Lrf_bar
	v_readlane_b32 s2, v254, 61
	s_lshl_b32 s2, s2, 8
	s_lshl_b32 s8, s17, 2
	s_add_i32 s2, s2, s8
	s_add_i32 s2, s2, 0x10000
	v_readlane_b32 s8, v255, 7
	v_readlane_b32 s9, v255, 8
	s_add_u32 s8, s8, s2
	s_addc_u32 s9, s9, 0
	s_mov_b64 s[14:15], exec
	s_mov_b64 exec, 1
	global_atomic_add v1, v226, s[8:9]
	s_mov_b64 exec, s[14:15]
	s_mov_b32 s2, 0
.Lrf_poll:
	global_load_dword v251, v1, s[8:9] sc1
	s_waitcnt vmcnt(0)
	v_readfirstlane_b32 s12, v251
	s_cmp_ge_u32 s12, 4
	s_cbranch_scc1 .Lrf_ok
	s_add_i32 s2, s2, 1
	s_cmp_gt_u32 s2, 0x20000
	s_cbranch_scc1 .Lrf_ok
	s_sleep 1
	s_branch .Lrf_poll

.Lrf_bar:
	s_barrier
	global_load_dwordx4 v[200:203], v253, s[10:11] offset:0
	global_load_dwordx4 v[204:207], v253, s[10:11] offset:256
	global_load_dwordx4 v[208:211], v253, s[10:11] offset:512
	global_load_dwordx4 v[212:215], v253, s[10:11] offset:768
	global_load_dwordx4 v[216:219], v253, s[10:11] offset:2048
	global_load_dwordx4 v[220:223], v253, s[10:11] offset:2304
	global_load_dwordx4 v[240:243], v253, s[10:11] offset:2560
	global_load_dwordx4 v[244:247], v253, s[10:11] offset:2816
	v_lshl_add_u32 v251, v236, 2, s68
	v_lshlrev_b32_e32 v251, 1, v251
	v_add_u32_e32 v249, s67, v235
	v_mul_u32_u24_e32 v249, 0x210, v249
	v_add_u32_e32 v251, v251, v249
	v_add_u32_e32 v252, 0x10800, v251
	s_mov_b32 s2, 0x3a800000
	s_waitcnt vmcnt(7)
	v_add_f32_e32 v200, v200, v201
	v_add_f32_e32 v202, v202, v203
	v_add_f32_e32 v200, v200, v202
	v_fma_f32 v200, v200, s2, v167
	v_rsq_f32_e32 v200, v200
	s_waitcnt vmcnt(6)
	v_add_f32_e32 v204, v204, v205
	v_add_f32_e32 v206, v206, v207
	v_add_f32_e32 v204, v204, v206
	v_fma_f32 v204, v204, s2, v167
	v_rsq_f32_e32 v204, v204
	s_waitcnt vmcnt(5)
	v_add_f32_e32 v208, v208, v209
	v_add_f32_e32 v210, v210, v211
	v_add_f32_e32 v208, v208, v210
	v_fma_f32 v208, v208, s2, v167
	v_rsq_f32_e32 v208, v208
	s_waitcnt vmcnt(4)
	v_add_f32_e32 v212, v212, v213
	v_add_f32_e32 v214, v214, v215
	v_add_f32_e32 v212, v212, v214
	v_fma_f32 v212, v212, s2, v167
	v_rsq_f32_e32 v212, v212
	s_waitcnt vmcnt(3)
	v_add_f32_e32 v216, v216, v217
	v_add_f32_e32 v218, v218, v219
	v_add_f32_e32 v216, v216, v218
	v_fma_f32 v216, v216, s2, v167
	v_rsq_f32_e32 v216, v216
	s_waitcnt vmcnt(2)
	v_add_f32_e32 v220, v220, v221
	v_add_f32_e32 v222, v222, v223
	v_add_f32_e32 v220, v220, v222
	v_fma_f32 v220, v220, s2, v167
	v_rsq_f32_e32 v220, v220
	s_waitcnt vmcnt(1)
	v_add_f32_e32 v240, v240, v241
	v_add_f32_e32 v242, v242, v243
	v_add_f32_e32 v240, v240, v242
	v_fma_f32 v240, v240, s2, v167
	v_rsq_f32_e32 v240, v240
	s_waitcnt vmcnt(0)
	v_add_f32_e32 v244, v244, v245
	v_add_f32_e32 v246, v246, v247
	v_add_f32_e32 v244, v244, v246
	v_fma_f32 v244, v244, s2, v167
	v_rsq_f32_e32 v244, v244
	s_nop 0
	v_mul_f32_e32 v126, v126, v200
	v_mul_f32_e32 v127, v127, v200
	v_mul_f32_e32 v128, v128, v200
	v_mul_f32_e32 v129, v129, v200
	v_fma_f32 v126, v126, v146, v162
	v_fma_f32 v127, v127, v147, v163
	v_fma_f32 v128, v128, v148, v164
	v_fma_f32 v129, v129, v149, v165
	v_cvt_pk_bf16_f32 v126, v126, v127
	v_cvt_pk_bf16_f32 v127, v128, v129
	v_mul_f32_e32 v122, v122, v200
	v_mul_f32_e32 v123, v123, v200
	v_mul_f32_e32 v124, v124, v200
	v_mul_f32_e32 v125, v125, v200
	v_fma_f32 v122, v122, v150, v188
	v_fma_f32 v123, v123, v151, v189
	v_fma_f32 v124, v124, v152, v190
	v_fma_f32 v125, v125, v153, v191
	v_cvt_pk_bf16_f32 v122, v122, v123
	v_cvt_pk_bf16_f32 v123, v124, v125
	v_mul_f32_e32 v118, v118, v200
	v_mul_f32_e32 v119, v119, v200
	v_mul_f32_e32 v120, v120, v200
	v_mul_f32_e32 v121, v121, v200
	v_fma_f32 v118, v118, v154, v192
	v_fma_f32 v119, v119, v155, v193
	v_fma_f32 v120, v120, v156, v194
	v_fma_f32 v121, v121, v157, v195
	v_cvt_pk_bf16_f32 v118, v118, v119
	v_cvt_pk_bf16_f32 v119, v120, v121
	v_mul_f32_e32 v114, v114, v200
	v_mul_f32_e32 v115, v115, v200
	v_mul_f32_e32 v116, v116, v200
	v_mul_f32_e32 v117, v117, v200
	v_fma_f32 v114, v114, v158, v196
	v_fma_f32 v115, v115, v159, v197
	v_fma_f32 v116, v116, v160, v198
	v_fma_f32 v117, v117, v161, v199
	v_cvt_pk_bf16_f32 v114, v114, v115
	v_cvt_pk_bf16_f32 v115, v116, v117
	ds_write_b64 v251, v[126:127] offset:0
	ds_write_b64 v251, v[122:123] offset:32
	ds_write_b64 v251, v[118:119] offset:256
	ds_write_b64 v251, v[114:115] offset:288
	v_mul_f32_e32 v110, v110, v204
	v_mul_f32_e32 v111, v111, v204
	v_mul_f32_e32 v112, v112, v204
	v_mul_f32_e32 v113, v113, v204
	v_fma_f32 v110, v110, v146, v162
	v_fma_f32 v111, v111, v147, v163
	v_fma_f32 v112, v112, v148, v164
	v_fma_f32 v113, v113, v149, v165
	v_cvt_pk_bf16_f32 v110, v110, v111
	v_cvt_pk_bf16_f32 v111, v112, v113
	v_mul_f32_e32 v106, v106, v204
	v_mul_f32_e32 v107, v107, v204
	v_mul_f32_e32 v108, v108, v204
	v_mul_f32_e32 v109, v109, v204
	v_fma_f32 v106, v106, v150, v188
	v_fma_f32 v107, v107, v151, v189
	v_fma_f32 v108, v108, v152, v190
	v_fma_f32 v109, v109, v153, v191
	v_cvt_pk_bf16_f32 v106, v106, v107
	v_cvt_pk_bf16_f32 v107, v108, v109
	v_mul_f32_e32 v102, v102, v204
	v_mul_f32_e32 v103, v103, v204
	v_mul_f32_e32 v104, v104, v204
	v_mul_f32_e32 v105, v105, v204
	v_fma_f32 v102, v102, v154, v192
	v_fma_f32 v103, v103, v155, v193
	v_fma_f32 v104, v104, v156, v194
	v_fma_f32 v105, v105, v157, v195
	v_cvt_pk_bf16_f32 v102, v102, v103
	v_cvt_pk_bf16_f32 v103, v104, v105
	v_mul_f32_e32 v98, v98, v204
	v_mul_f32_e32 v99, v99, v204
	v_mul_f32_e32 v100, v100, v204
	v_mul_f32_e32 v101, v101, v204
	v_fma_f32 v98, v98, v158, v196
	v_fma_f32 v99, v99, v159, v197
	v_fma_f32 v100, v100, v160, v198
	v_fma_f32 v101, v101, v161, v199
	v_cvt_pk_bf16_f32 v98, v98, v99
	v_cvt_pk_bf16_f32 v99, v100, v101
	ds_write_b64 v251, v[110:111] offset:8448
	ds_write_b64 v251, v[106:107] offset:8480
	ds_write_b64 v251, v[102:103] offset:8704
	ds_write_b64 v251, v[98:99] offset:8736
	v_mul_f32_e32 v94, v94, v208
	v_mul_f32_e32 v95, v95, v208
	v_mul_f32_e32 v96, v96, v208
	v_mul_f32_e32 v97, v97, v208
	v_fma_f32 v94, v94, v146, v162
	v_fma_f32 v95, v95, v147, v163
	v_fma_f32 v96, v96, v148, v164
	v_fma_f32 v97, v97, v149, v165
	v_cvt_pk_bf16_f32 v94, v94, v95
	v_cvt_pk_bf16_f32 v95, v96, v97
	v_mul_f32_e32 v90, v90, v208
	v_mul_f32_e32 v91, v91, v208
	v_mul_f32_e32 v92, v92, v208
	v_mul_f32_e32 v93, v93, v208
	v_fma_f32 v90, v90, v150, v188
	v_fma_f32 v91, v91, v151, v189
	v_fma_f32 v92, v92, v152, v190
	v_fma_f32 v93, v93, v153, v191
	v_cvt_pk_bf16_f32 v90, v90, v91
	v_cvt_pk_bf16_f32 v91, v92, v93
	v_mul_f32_e32 v86, v86, v208
	v_mul_f32_e32 v87, v87, v208
	v_mul_f32_e32 v88, v88, v208
	v_mul_f32_e32 v89, v89, v208
	v_fma_f32 v86, v86, v154, v192
	v_fma_f32 v87, v87, v155, v193
	v_fma_f32 v88, v88, v156, v194
	v_fma_f32 v89, v89, v157, v195
	v_cvt_pk_bf16_f32 v86, v86, v87
	v_cvt_pk_bf16_f32 v87, v88, v89
	v_mul_f32_e32 v82, v82, v208
	v_mul_f32_e32 v83, v83, v208
	v_mul_f32_e32 v84, v84, v208
	v_mul_f32_e32 v85, v85, v208
	v_fma_f32 v82, v82, v158, v196
	v_fma_f32 v83, v83, v159, v197
	v_fma_f32 v84, v84, v160, v198
	v_fma_f32 v85, v85, v161, v199
	v_cvt_pk_bf16_f32 v82, v82, v83
	v_cvt_pk_bf16_f32 v83, v84, v85
	ds_write_b64 v251, v[94:95] offset:16896
	ds_write_b64 v251, v[90:91] offset:16928
	ds_write_b64 v251, v[86:87] offset:17152
	ds_write_b64 v251, v[82:83] offset:17184
	v_mul_f32_e32 v78, v78, v212
	v_mul_f32_e32 v79, v79, v212
	v_mul_f32_e32 v80, v80, v212
	v_mul_f32_e32 v81, v81, v212
	v_fma_f32 v78, v78, v146, v162
	v_fma_f32 v79, v79, v147, v163
	v_fma_f32 v80, v80, v148, v164
	v_fma_f32 v81, v81, v149, v165
	v_cvt_pk_bf16_f32 v78, v78, v79
	v_cvt_pk_bf16_f32 v79, v80, v81
	v_mul_f32_e32 v74, v74, v212
	v_mul_f32_e32 v75, v75, v212
	v_mul_f32_e32 v76, v76, v212
	v_mul_f32_e32 v77, v77, v212
	v_fma_f32 v74, v74, v150, v188
	v_fma_f32 v75, v75, v151, v189
	v_fma_f32 v76, v76, v152, v190
	v_fma_f32 v77, v77, v153, v191
	v_cvt_pk_bf16_f32 v74, v74, v75
	v_cvt_pk_bf16_f32 v75, v76, v77
	v_mul_f32_e32 v70, v70, v212
	v_mul_f32_e32 v71, v71, v212
	v_mul_f32_e32 v72, v72, v212
	v_mul_f32_e32 v73, v73, v212
	v_fma_f32 v70, v70, v154, v192
	v_fma_f32 v71, v71, v155, v193
	v_fma_f32 v72, v72, v156, v194
	v_fma_f32 v73, v73, v157, v195
	v_cvt_pk_bf16_f32 v70, v70, v71
	v_cvt_pk_bf16_f32 v71, v72, v73
	v_mul_f32_e32 v66, v66, v212
	v_mul_f32_e32 v67, v67, v212
	v_mul_f32_e32 v68, v68, v212
	v_mul_f32_e32 v69, v69, v212
	v_fma_f32 v66, v66, v158, v196
	v_fma_f32 v67, v67, v159, v197
	v_fma_f32 v68, v68, v160, v198
	v_fma_f32 v69, v69, v161, v199
	v_cvt_pk_bf16_f32 v66, v66, v67
	v_cvt_pk_bf16_f32 v67, v68, v69
	ds_write_b64 v251, v[78:79] offset:25344
	ds_write_b64 v251, v[74:75] offset:25376
	ds_write_b64 v251, v[70:71] offset:25600
	ds_write_b64 v251, v[66:67] offset:25632
	v_mul_f32_e32 v62, v62, v216
	v_mul_f32_e32 v63, v63, v216
	v_mul_f32_e32 v64, v64, v216
	v_mul_f32_e32 v65, v65, v216
	v_fma_f32 v62, v62, v146, v162
	v_fma_f32 v63, v63, v147, v163
	v_fma_f32 v64, v64, v148, v164
	v_fma_f32 v65, v65, v149, v165
	v_cvt_pk_bf16_f32 v62, v62, v63
	v_cvt_pk_bf16_f32 v63, v64, v65
	v_mul_f32_e32 v58, v58, v216
	v_mul_f32_e32 v59, v59, v216
	v_mul_f32_e32 v60, v60, v216
	v_mul_f32_e32 v61, v61, v216
	v_fma_f32 v58, v58, v150, v188
	v_fma_f32 v59, v59, v151, v189
	v_fma_f32 v60, v60, v152, v190
	v_fma_f32 v61, v61, v153, v191
	v_cvt_pk_bf16_f32 v58, v58, v59
	v_cvt_pk_bf16_f32 v59, v60, v61
	v_mul_f32_e32 v54, v54, v216
	v_mul_f32_e32 v55, v55, v216
	v_mul_f32_e32 v56, v56, v216
	v_mul_f32_e32 v57, v57, v216
	v_fma_f32 v54, v54, v154, v192
	v_fma_f32 v55, v55, v155, v193
	v_fma_f32 v56, v56, v156, v194
	v_fma_f32 v57, v57, v157, v195
	v_cvt_pk_bf16_f32 v54, v54, v55
	v_cvt_pk_bf16_f32 v55, v56, v57
	v_mul_f32_e32 v50, v50, v216
	v_mul_f32_e32 v51, v51, v216
	v_mul_f32_e32 v52, v52, v216
	v_mul_f32_e32 v53, v53, v216
	v_fma_f32 v50, v50, v158, v196
	v_fma_f32 v51, v51, v159, v197
	v_fma_f32 v52, v52, v160, v198
	v_fma_f32 v53, v53, v161, v199
	v_cvt_pk_bf16_f32 v50, v50, v51
	v_cvt_pk_bf16_f32 v51, v52, v53
	ds_write_b64 v252, v[62:63] offset:0
	ds_write_b64 v252, v[58:59] offset:32
	ds_write_b64 v252, v[54:55] offset:256
	ds_write_b64 v252, v[50:51] offset:288
	v_mul_f32_e32 v46, v46, v220
	v_mul_f32_e32 v47, v47, v220
	v_mul_f32_e32 v48, v48, v220
	v_mul_f32_e32 v49, v49, v220
	v_fma_f32 v46, v46, v146, v162
	v_fma_f32 v47, v47, v147, v163
	v_fma_f32 v48, v48, v148, v164
	v_fma_f32 v49, v49, v149, v165
	v_cvt_pk_bf16_f32 v46, v46, v47
	v_cvt_pk_bf16_f32 v47, v48, v49
	v_mul_f32_e32 v42, v42, v220
	v_mul_f32_e32 v43, v43, v220
	v_mul_f32_e32 v44, v44, v220
	v_mul_f32_e32 v45, v45, v220
	v_fma_f32 v42, v42, v150, v188
	v_fma_f32 v43, v43, v151, v189
	v_fma_f32 v44, v44, v152, v190
	v_fma_f32 v45, v45, v153, v191
	v_cvt_pk_bf16_f32 v42, v42, v43
	v_cvt_pk_bf16_f32 v43, v44, v45
	v_mul_f32_e32 v38, v38, v220
	v_mul_f32_e32 v39, v39, v220
	v_mul_f32_e32 v40, v40, v220
	v_mul_f32_e32 v41, v41, v220
	v_fma_f32 v38, v38, v154, v192
	v_fma_f32 v39, v39, v155, v193
	v_fma_f32 v40, v40, v156, v194
	v_fma_f32 v41, v41, v157, v195
	v_cvt_pk_bf16_f32 v38, v38, v39
	v_cvt_pk_bf16_f32 v39, v40, v41
	v_mul_f32_e32 v34, v34, v220
	v_mul_f32_e32 v35, v35, v220
	v_mul_f32_e32 v36, v36, v220
	v_mul_f32_e32 v37, v37, v220
	v_fma_f32 v34, v34, v158, v196
	v_fma_f32 v35, v35, v159, v197
	v_fma_f32 v36, v36, v160, v198
	v_fma_f32 v37, v37, v161, v199
	v_cvt_pk_bf16_f32 v34, v34, v35
	v_cvt_pk_bf16_f32 v35, v36, v37
	ds_write_b64 v252, v[46:47] offset:8448
	ds_write_b64 v252, v[42:43] offset:8480
	ds_write_b64 v252, v[38:39] offset:8704
	ds_write_b64 v252, v[34:35] offset:8736
	v_mul_f32_e32 v30, v30, v240
	v_mul_f32_e32 v31, v31, v240
	v_mul_f32_e32 v32, v32, v240
	v_mul_f32_e32 v33, v33, v240
	v_fma_f32 v30, v30, v146, v162
	v_fma_f32 v31, v31, v147, v163
	v_fma_f32 v32, v32, v148, v164
	v_fma_f32 v33, v33, v149, v165
	v_cvt_pk_bf16_f32 v30, v30, v31
	v_cvt_pk_bf16_f32 v31, v32, v33
	v_mul_f32_e32 v26, v26, v240
	v_mul_f32_e32 v27, v27, v240
	v_mul_f32_e32 v28, v28, v240
	v_mul_f32_e32 v29, v29, v240
	v_fma_f32 v26, v26, v150, v188
	v_fma_f32 v27, v27, v151, v189
	v_fma_f32 v28, v28, v152, v190
	v_fma_f32 v29, v29, v153, v191
	v_cvt_pk_bf16_f32 v26, v26, v27
	v_cvt_pk_bf16_f32 v27, v28, v29
	v_mul_f32_e32 v22, v22, v240
	v_mul_f32_e32 v23, v23, v240
	v_mul_f32_e32 v24, v24, v240
	v_mul_f32_e32 v25, v25, v240
	v_fma_f32 v22, v22, v154, v192
	v_fma_f32 v23, v23, v155, v193
	v_fma_f32 v24, v24, v156, v194
	v_fma_f32 v25, v25, v157, v195
	v_cvt_pk_bf16_f32 v22, v22, v23
	v_cvt_pk_bf16_f32 v23, v24, v25
	v_mul_f32_e32 v18, v18, v240
	v_mul_f32_e32 v19, v19, v240
	v_mul_f32_e32 v20, v20, v240
	v_mul_f32_e32 v21, v21, v240
	v_fma_f32 v18, v18, v158, v196
	v_fma_f32 v19, v19, v159, v197
	v_fma_f32 v20, v20, v160, v198
	v_fma_f32 v21, v21, v161, v199
	v_cvt_pk_bf16_f32 v18, v18, v19
	v_cvt_pk_bf16_f32 v19, v20, v21
	ds_write_b64 v252, v[30:31] offset:16896
	ds_write_b64 v252, v[26:27] offset:16928
	ds_write_b64 v252, v[22:23] offset:17152
	ds_write_b64 v252, v[18:19] offset:17184
	v_mul_f32_e32 v14, v14, v244
	v_mul_f32_e32 v15, v15, v244
	v_mul_f32_e32 v16, v16, v244
	v_mul_f32_e32 v17, v17, v244
	v_fma_f32 v14, v14, v146, v162
	v_fma_f32 v15, v15, v147, v163
	v_fma_f32 v16, v16, v148, v164
	v_fma_f32 v17, v17, v149, v165
	v_cvt_pk_bf16_f32 v14, v14, v15
	v_cvt_pk_bf16_f32 v15, v16, v17
	v_mul_f32_e32 v10, v10, v244
	v_mul_f32_e32 v11, v11, v244
	v_mul_f32_e32 v12, v12, v244
	v_mul_f32_e32 v13, v13, v244
	v_fma_f32 v10, v10, v150, v188
	v_fma_f32 v11, v11, v151, v189
	v_fma_f32 v12, v12, v152, v190
	v_fma_f32 v13, v13, v153, v191
	v_cvt_pk_bf16_f32 v10, v10, v11
	v_cvt_pk_bf16_f32 v11, v12, v13
	v_mul_f32_e32 v6, v6, v244
	v_mul_f32_e32 v7, v7, v244
	v_mul_f32_e32 v8, v8, v244
	v_mul_f32_e32 v9, v9, v244
	v_fma_f32 v6, v6, v154, v192
	v_fma_f32 v7, v7, v155, v193
	v_fma_f32 v8, v8, v156, v194
	v_fma_f32 v9, v9, v157, v195
	v_cvt_pk_bf16_f32 v6, v6, v7
	v_cvt_pk_bf16_f32 v7, v8, v9
	v_mul_f32_e32 v2, v2, v244
	v_mul_f32_e32 v3, v3, v244
	v_mul_f32_e32 v4, v4, v244
	v_mul_f32_e32 v5, v5, v244
	v_fma_f32 v2, v2, v158, v196
	v_fma_f32 v3, v3, v159, v197
	v_fma_f32 v4, v4, v160, v198
	v_fma_f32 v5, v5, v161, v199
	v_cvt_pk_bf16_f32 v2, v2, v3
	v_cvt_pk_bf16_f32 v3, v4, v5
	ds_write_b64 v252, v[14:15] offset:25344
	ds_write_b64 v252, v[10:11] offset:25376
	ds_write_b64 v252, v[6:7] offset:25600
	ds_write_b64 v252, v[2:3] offset:25632
	v_lshl_add_u32 v249, v236, 4, v235
	v_lshrrev_b32_e32 v250, 5, v249
	v_and_b32_e32 v249, 31, v249
	v_lshlrev_b32_e32 v249, 4, v249
	v_lshl_add_u32 v250, s3, 5, v250
	v_mul_u32_u24_e32 v251, 0x210, v250
	v_add_u32_e32 v251, v251, v249
	v_lshl_add_u32 v248, v250, 11, v249
	v_readlane_b32 s12, v255, 9
	v_readlane_b32 s13, v255, 10
	s_lshl_b32 s2, s17, 19
	s_lshl_b32 s8, s48, 9
	s_add_i32 s2, s2, s8
	s_add_u32 s12, s12, s2
	s_addc_u32 s13, s13, 0
	s_waitcnt lgkmcnt(0)
	s_barrier
	ds_read_b128 v[2:5], v251 offset:0
	ds_read_b128 v[6:9], v251 offset:1056
	ds_read_b128 v[10:13], v251 offset:2112
	ds_read_b128 v[14:17], v251 offset:3168
	ds_read_b128 v[18:21], v251 offset:4224
	ds_read_b128 v[22:25], v251 offset:5280
	ds_read_b128 v[26:29], v251 offset:6336
	ds_read_b128 v[30:33], v251 offset:7392
	ds_read_b128 v[34:37], v251 offset:8448
	ds_read_b128 v[38:41], v251 offset:9504
	ds_read_b128 v[42:45], v251 offset:10560
	ds_read_b128 v[46:49], v251 offset:11616
	ds_read_b128 v[50:53], v251 offset:12672
	ds_read_b128 v[54:57], v251 offset:13728
	ds_read_b128 v[58:61], v251 offset:14784
	ds_read_b128 v[62:65], v251 offset:15840
	s_waitcnt lgkmcnt(15)
	global_store_dwordx4 v248, v[2:5], s[12:13]
	s_waitcnt lgkmcnt(14)
	s_add_u32 s14, s12, 0x1000
	s_addc_u32 s15, s13, 0
	global_store_dwordx4 v248, v[6:9], s[14:15]
	s_waitcnt lgkmcnt(13)
	s_add_u32 s14, s12, 0x2000
	s_addc_u32 s15, s13, 0
	global_store_dwordx4 v248, v[10:13], s[14:15]
	s_waitcnt lgkmcnt(12)
	s_add_u32 s14, s12, 0x3000
	s_addc_u32 s15, s13, 0
	global_store_dwordx4 v248, v[14:17], s[14:15]
	s_waitcnt lgkmcnt(11)
	s_add_u32 s14, s12, 0x4000
	s_addc_u32 s15, s13, 0
	global_store_dwordx4 v248, v[18:21], s[14:15]
	s_waitcnt lgkmcnt(10)
	s_add_u32 s14, s12, 0x5000
	s_addc_u32 s15, s13, 0
	global_store_dwordx4 v248, v[22:25], s[14:15]
	s_waitcnt lgkmcnt(9)
	s_add_u32 s14, s12, 0x6000
	s_addc_u32 s15, s13, 0
	global_store_dwordx4 v248, v[26:29], s[14:15]
	s_waitcnt lgkmcnt(8)
	s_add_u32 s14, s12, 0x7000
	s_addc_u32 s15, s13, 0
	global_store_dwordx4 v248, v[30:33], s[14:15]
	s_waitcnt lgkmcnt(7)
	s_add_u32 s14, s12, 0x8000
	s_addc_u32 s15, s13, 0
	global_store_dwordx4 v248, v[34:37], s[14:15]
	s_waitcnt lgkmcnt(6)
	s_add_u32 s14, s12, 0x9000
	s_addc_u32 s15, s13, 0
	global_store_dwordx4 v248, v[38:41], s[14:15]
	s_waitcnt lgkmcnt(5)
	s_add_u32 s14, s12, 0xa000
	s_addc_u32 s15, s13, 0
	global_store_dwordx4 v248, v[42:45], s[14:15]
	s_waitcnt lgkmcnt(4)
	s_add_u32 s14, s12, 0xb000
	s_addc_u32 s15, s13, 0
	global_store_dwordx4 v248, v[46:49], s[14:15]
	s_waitcnt lgkmcnt(3)
	s_add_u32 s14, s12, 0xc000
	s_addc_u32 s15, s13, 0
	global_store_dwordx4 v248, v[50:53], s[14:15]
	s_waitcnt lgkmcnt(2)
	s_add_u32 s14, s12, 0xd000
	s_addc_u32 s15, s13, 0
	global_store_dwordx4 v248, v[54:57], s[14:15]
	s_waitcnt lgkmcnt(1)
	s_add_u32 s14, s12, 0xe000
	s_addc_u32 s15, s13, 0
	global_store_dwordx4 v248, v[58:61], s[14:15]
	s_waitcnt lgkmcnt(0)
	s_add_u32 s14, s12, 0xf000
	s_addc_u32 s15, s13, 0
	global_store_dwordx4 v248, v[62:65], s[14:15]
	s_branch .LBB0_561

.LBB0_893:
	s_cmpk_lt_i32 s67, 192
	s_cbranch_scc1 .Ladh_skip
	v_readlane_b32 s1, v254, 61
	s_mov_b32 s20, 0
	s_cmp_eq_u32 s1, 3
	s_cselect_b32 s20, 1, s20
	s_cmp_eq_u32 s1, 12
	s_cselect_b32 s20, 2, s20
	s_cmp_eq_u32 s1, 20
	s_cselect_b32 s20, 3, s20
	s_cmp_eq_u32 s20, 0
	s_cbranch_scc1 .Ladh_skip
	v_readlane_b32 s0, v254, 63
	s_sub_i32 s3, s67, 192
	s_load_dwordx4 s[8:11], s[60:61], 0x38
	s_load_dwordx4 s[12:15], s[60:61], 0x48
	v_mbcnt_lo_u32_b32 v0, -1, 0
	v_mbcnt_hi_u32_b32 v0, -1, v0
	s_lshl_b32 s16, s0, 14
	s_lshl_b32 s1, s0, 9
	v_lshl_add_u32 v18, v0, 2, s1
	v_lshl_add_u32 v19, v0, 4, s16
	s_waitcnt lgkmcnt(0)
	s_add_u32 s6, s8, 0x1000
	s_addc_u32 s7, s9, 0
	global_load_dword v26, v18, s[10:11]
	global_load_dword v27, v18, s[10:11] offset:256
	global_load_dword v28, v18, s[8:9]
	global_load_dword v29, v18, s[8:9] offset:256
	global_load_dword v30, v18, s[6:7]
	global_load_dword v31, v18, s[6:7] offset:256
	s_waitcnt vmcnt(0)
	v_mul_f32_e32 v74, 0xbfb8aa3b, v26
	v_mul_f32_e32 v75, 0xbfb8aa3b, v27
	v_mul_f32_e32 v76, 0xbfb8aa3b, v28
	v_mul_f32_e32 v77, 0xbfb8aa3b, v29
	v_mul_f32_e32 v78, 0xbfb8aa3b, v30
	v_mul_f32_e32 v79, 0xbfb8aa3b, v31
	v_exp_f32_e32 v74, v74
	v_exp_f32_e32 v75, v75
	v_exp_f32_e32 v76, v76
	v_exp_f32_e32 v77, v77
	v_exp_f32_e32 v78, v78
	v_exp_f32_e32 v79, v79
	v_add_f32_e32 v74, 1.0, v74
	v_add_f32_e32 v75, 1.0, v75
	v_add_f32_e32 v76, 1.0, v76
	v_add_f32_e32 v77, 1.0, v77
	v_add_f32_e32 v78, 1.0, v78
	v_add_f32_e32 v79, 1.0, v79
	v_rcp_f32_e32 v74, v74
	v_rcp_f32_e32 v75, v75
	v_rcp_f32_e32 v76, v76
	v_rcp_f32_e32 v77, v77
	v_rcp_f32_e32 v78, v78
	v_rcp_f32_e32 v79, v79
	v_mul_f32_e32 v26, v26, v74
	v_mul_f32_e32 v27, v27, v75
	v_mul_f32_e32 v28, v28, v76
	v_mul_f32_e32 v29, v29, v77
	v_mul_f32_e32 v30, v30, v78
	v_mul_f32_e32 v31, v31, v79
	v_mov_b32_e32 v90, v26
	v_mov_b32_e32 v91, v28
	v_mov_b32_e32 v92, v30
	v_mov_b32_e32 v93, 0
	v_mov_b32_e32 v94, v27
	v_mov_b32_e32 v95, v29
	v_mov_b32_e32 v96, v31
	v_mov_b32_e32 v97, 0
	ds_write_b128 v19, v[90:93]
	ds_write_b128 v19, v[94:97] offset:1024
	v_lshrrev_b32_e32 v20, 3, v0
	v_and_b32_e32 v21, 7, v0
	v_mul_u32_u24_e32 v22, 0x9000, v20
	v_lshl_add_u32 v22, v21, 4, v22
	s_mul_i32 s17, s0, 0x480000
	s_mul_i32 s1, s20, 0x2400000
	s_add_u32 s17, s17, s1
	s_add_u32 s12, s12, s17
	s_addc_u32 s13, s13, 0
	s_mul_i32 s1, s20, 0x9000
	s_add_u32 s14, s14, s1
	s_addc_u32 s15, s15, 0
	v_lshl_add_u32 v23, v20, 4, s16
	s_mul_i32 s17, s0, 0x180
	s_add_i32 s17, s17, 131072
	v_readlane_b32 s8, v255, 7
	v_readlane_b32 s9, v255, 8
	s_mul_i32 s1, s20, 0x1b000
	s_add_i32 s1, s1, 0x100000
	s_add_u32 s8, s8, s1
	s_addc_u32 s9, s9, 0
	s_mov_b32 s18, s3
	s_waitcnt lgkmcnt(0)
	v_lshl_add_u32 v94, v21, 4, s17
	s_mov_b32 s17, 131072
	v_lshl_add_u32 v95, v0, 2, s17
	v_lshlrev_b32_e32 v96, 2, v0

PROG:
	.byte	0, 0, 1
	.byte	1, 0, 1
	.byte	3, 0, 1
	.byte	4, 0, 1
	.byte	1, 1, 1
	.byte	5, 0, 1
	.byte	6, 0, 1
	.byte	7, 0, 1
	.byte	8, 0, 1
	.byte	3, 1, 1
	.byte	4, 1, 1
	.byte	3, 2, 1
	.byte	4, 2, 1
	.byte	2, 5, 1
	.byte	9, 0, 0
	.byte	10, 0, 1
	.byte	11, 0, 1
	.byte	8, 1, 0
	.byte	1, 6, 1
	.byte	3, 3, 1
	.byte	4, 3, 1
	.byte	3, 4, 1
	.byte	4, 4, 1
	.byte	12, 0, 1
	.byte	13, 0, 1
	.byte	14, 0, 1
	.byte	8, 2, 1
	.byte	3, 5, 1
	.byte	4, 5, 1
	.byte	3, 6, 1
	.byte	4, 6, 1
	.byte	15, 0, 1
	.byte	16, 0, 1
	.byte	8, 3, 1
	.byte	3, 7, 1
	.byte	4, 7, 1
	.byte	17, 0, 0
	.size	PROG, 111

	.protected	BGTAB
	.type	BGTAB,@object
	.globl	BGTAB
	.p2align	4, 0x0
BGTAB:
	.long	0, 0, 0, 0
	.long	0, 0, 0, 0
	.long	2816, 8448, 0, 0
	.long	8448, 12672, 33792, 36352
	.long	0, 0, 0, 0
	.long	0, 0, 0, 0
	.long	0, 0, 0, 0
	.long	0, 0, 0, 0
	.long	0, 0, 0, 0
	.long	12672, 16896, 36352, 36864
	.long	16896, 21120, 40448, 40960
	.long	21120, 25344, 36864, 38400
	.long	25344, 29568, 0, 0
	.long	0, 0, 0, 0
	.long	0, 0, 0, 0
	.long	0, 0, 0, 0
	.long	0, 0, 0, 0
	.long	0, 0, 0, 0
	.long	0, 0, 0, 0
	.long	29568, 33792, 38400, 40448
	.long	0, 0, 0, 0
	.long	0, 0, 0, 0
	.long	0, 0, 0, 0
	.long	0, 0, 0, 0
	.long	0, 0, 0, 0
	.long	0, 0, 0, 0
	.long	0, 0, 0, 0
	.long	0, 0, 0, 0
	.long	0, 0, 0, 0
	.long	0, 0, 0, 0
	.long	0, 0, 0, 0
	.long	0, 0, 0, 0
	.long	0, 0, 0, 0
	.long	0, 0, 0, 0
	.long	0, 0, 0, 0
	.long	0, 0, 0, 0
	.long	0, 0, 0, 0
	.size	BGTAB, 592

	.type	__hip_cuid_dfa6192372e94434,@object
